# mnorm: L2-warming loads three tokens ahead (extra loads left outstanding, counted waits raised)
# baseline (speedup 1.0000x reference)
; #define MN_LOAD(tk_) do { const int s_ = (tk_) & (SEQL - 1); hr = *(const u32x2*)(Hm + (size_t)(tk_) * 2048 + c); zr = *(const u32x2*)(Y0 + (size_t)(tk_) * 4096 + 2048 + c); \
;             _Pragma("unroll") for (int j = 0; j < 4; ++j) xr[j] = (s_ - 3 + j >= 0) ? *(const u32x2*)(XM + (size_t)((tk_) - 3 + j) * 2048 + c) : (u32x2){0u, 0u}; } while (0)
; __device__ void mnorm_phase(const Params& p) {
;     ...
;     for (int blk = blockIdx.x; blk < 256; blk += gridDim.x) {
;         u32x2 hr, xr[4], zr;
;     ...
;         MN_LOAD(blk * 64);
; #pragma unroll 2
;         for (int tt = 0; tt < 64; ++tt) {
;             const int tk = blk * 64 + tt;
;             const u32x2 hc_ = hr, zc_ = zr; const u32x2 xc0 = xr[0], xc1 = xr[1], xc2 = xr[2], xc3 = xr[3];
;             if (tt < 63) MN_LOAD(tk + 1);
.LBB0_601:
	global_load_dwordx2 v[60:61], v[52:53], off
	s_mov_b32 s30, s13
	s_add_i32 s30, s30, 3
	s_min_i32 s30, s30, 0x3fff
	s_ashr_i32 s31, s30, 31
	s_lshl_b64 s[32:33], s[30:31], 12
	s_lshl_b64 s[34:35], s[30:31], 13
	s_add_u32 s34, s10, s34
	s_addc_u32 s35, s12, s35
	s_add_u32 s34, s34, 0x1000
	s_addc_u32 s35, s35, 0
	v_lshl_add_u64 v[100:101], v[30:31], 0, s[32:33]
	v_lshl_add_u64 v[102:103], v[32:33], 0, s[32:33]
	v_lshl_add_u64 v[104:105], s[34:35], 0, v[26:27]
	global_load_dwordx2 v[106:107], v[100:101], off
	global_load_dwordx2 v[108:109], v[102:103], off
	global_load_dwordx2 v[110:111], v[104:105], off
	s_mov_b32 s8, 0
	s_branch .LBB0_605

; __device__ __forceinline__ unsigned pk2(float lo, float hi) { unsigned r; asm volatile("v_cvt_pk_bf16_f32 %0, %1, %2" : "=v"(r) : "v"(lo), "v"(hi)); return r; }
; __device__ __forceinline__ float bflo(unsigned w) { return __uint_as_float(w << 16); }
; __device__ __forceinline__ float bfhi(unsigned w) { return __uint_as_float(w & 0xffff0000u); }
; __device__ __forceinline__ float fsig0(float x) { return __builtin_amdgcn_rcpf(1.0f + __expf(-x)); }
; #define MN_LOAD(tk_) do { const int s_ = (tk_) & (SEQL - 1); hr = *(const u32x2*)(Hm + (size_t)(tk_) * 2048 + c); zr = *(const u32x2*)(Y0 + (size_t)(tk_) * 4096 + 2048 + c); \
;             _Pragma("unroll") for (int j = 0; j < 4; ++j) xr[j] = (s_ - 3 + j >= 0) ? *(const u32x2*)(XM + (size_t)((tk_) - 3 + j) * 2048 + c) : (u32x2){0u, 0u}; } while (0)
; __device__ void mnorm_phase(const Params& p) {
;     ...
;         for (int tt = 0; tt < 64; ++tt) {
;             const int tk = blk * 64 + tt;
;             const u32x2 hc_ = hr, zc_ = zr; const u32x2 xc0 = xr[0], xc1 = xr[1], xc2 = xr[2], xc3 = xr[3];
;             if (tt < 63) MN_LOAD(tk + 1);
;             float hv[4] = {bflo(hc_.x), bfhi(hc_.x), bflo(hc_.y), bfhi(hc_.y)};
;             const float mu = wave_sum_dpp(hv[0] + hv[1] + hv[2] + hv[3]) * (1.0f / 256.0f);
;             float d[4], sq = 0.f;
; #pragma unroll
;             for (int i = 0; i < 4; ++i) { d[i] = hv[i] - mu; sq += d[i] * d[i]; }
;             const float rs = rsqrtf(wave_sum_dpp(sq) * (1.0f / 256.0f) + 1e-6f);
;             float xmc[4] = {cbv[0], cbv[1], cbv[2], cbv[3]};
;             const u32x2 xs[4] = {xc0, xc1, xc2, xc3};
; #pragma unroll
;             for (int j = 0; j < 4; ++j) { xmc[0] += cw[j][0] * bflo(xs[j].x); xmc[1] += cw[j][1] * bfhi(xs[j].x); xmc[2] += cw[j][2] * bflo(xs[j].y); xmc[3] += cw[j][3] * bfhi(xs[j].y); }
;             const float z[4] = {bflo(zc_.x), bfhi(zc_.x), bflo(zc_.y), bfhi(zc_.y)};
;             float o[4];
; #pragma unroll
;             for (int i = 0; i < 4; ++i) o[i] = (d[i] * rs * gn[i] + skip[i] * xmc[i] * fsig0(xmc[i])) * z[i] * fsig0(z[i]);
;             u32x2 w; w.x = pk2(o[0], o[1]); w.y = pk2(o[2], o[3]); *(u32x2*)(Y0 + (size_t)tk * 4096 + 2048 + c) = w;
;         }
.LBB0_604:
	s_add_i32 s30, s13, s8
	s_add_i32 s30, s30, 5
	s_min_i32 s30, s30, 0x3fff
	s_ashr_i32 s31, s30, 31
	s_lshl_b64 s[32:33], s[30:31], 12
	s_lshl_b64 s[34:35], s[30:31], 13
	s_add_u32 s34, s10, s34
	s_addc_u32 s35, s12, s35
	s_add_u32 s34, s34, 0x1000
	s_addc_u32 s35, s35, 0
	v_lshl_add_u64 v[100:101], v[30:31], 0, s[32:33]
	v_lshl_add_u64 v[102:103], v[32:33], 0, s[32:33]
	v_lshl_add_u64 v[104:105], s[34:35], 0, v[26:27]
	global_load_dwordx2 v[106:107], v[100:101], off
	global_load_dwordx2 v[108:109], v[102:103], off
	global_load_dwordx2 v[110:111], v[104:105], off
	v_lshlrev_b32_e32 v75, 16, v70
	v_and_b32_e32 v77, 0xffff0000, v70
	v_lshlrev_b32_e32 v81, 16, v71
	v_add_f32_e32 v2, v75, v77
	v_and_b32_e32 v71, 0xffff0000, v71
	v_add_f32_e32 v2, v2, v81
	v_add_f32_e32 v2, v2, v71
	v_and_b32_e32 v85, 0xffff0000, v66
	v_and_b32_e32 v84, 0xffff0000, v62
	v_add_f32_dpp v2, v2, v2 quad_perm:[1,0,3,2] row_mask:0xf bank_mask:0xf bound_ctrl:1
	v_and_b32_e32 v7, 0xffff0000, v69
	v_pk_mul_f32 v[84:85], v[14:15], v[84:85]
	v_add_f32_dpp v2, v2, v2 quad_perm:[2,3,0,1] row_mask:0xf bank_mask:0xf bound_ctrl:1
	v_mov_b32_e32 v86, v84
	v_lshlrev_b32_e32 v89, 16, v67
	v_add_f32_dpp v2, v2, v2 row_half_mirror row_mask:0xf bank_mask:0xf bound_ctrl:1
	v_lshlrev_b32_e32 v88, 16, v63
	v_mov_b32_e32 v28, v85
	v_add_f32_dpp v2, v2, v2 row_mirror row_mask:0xf bank_mask:0xf bound_ctrl:1
	v_pk_mul_f32 v[88:89], v[44:45], v[88:89]
	v_readlane_b32 s3, v2, 16
	v_readlane_b32 s2, v2, 0
	v_and_b32_e32 v67, 0xffff0000, v67
	v_mov_b32_e32 v4, s3
	v_add_f32_e32 v83, s2, v4
	v_readlane_b32 s2, v2, 32
	v_and_b32_e32 v4, 0xffff0000, v68
	v_readlane_b32 s3, v2, 48
	v_lshlrev_b32_e32 v2, 16, v68
	v_mul_f32_e32 v82, v19, v4
	v_lshlrev_b32_e32 v4, 16, v69
	v_lshlrev_b32_e32 v69, 16, v66
	v_lshlrev_b32_e32 v68, 16, v62
	v_mov_b32_e32 v43, s2
	v_fma_f32 v2, v18, v2, v10
	v_pk_mul_f32 v[68:69], v[46:47], v[68:69]
	v_pk_add_f32 v[82:83], v[42:43], v[82:83]
	v_mov_b32_e32 v87, s3
	v_fma_f32 v4, v20, v4, v12
	v_add_f32_e32 v2, v2, v68
	v_pk_add_f32 v[82:83], v[82:83], v[86:87]
	v_and_b32_e32 v66, 0xffff0000, v63
	v_fma_f32 v7, v21, v7, v13
	v_add_f32_e32 v68, v2, v69
	v_pk_mul_f32 v[86:87], v[82:83], v[28:29]
	v_add_f32_e32 v2, v4, v88
	v_pk_mul_f32 v[62:63], v[16:17], v[66:67]
	v_add_f32_e32 v86, v2, v89
	v_add_f32_e32 v2, v7, v62
	v_add_f32_e32 v62, v2, v63
	v_lshlrev_b32_e32 v2, 16, v64
	v_mul_f32_e32 v74, v22, v2
	v_and_b32_e32 v2, 0xffff0000, v64
	v_mul_f32_e32 v76, v23, v2
	v_lshlrev_b32_e32 v2, 16, v65
	v_mul_f32_e32 v80, v24, v2
	v_and_b32_e32 v2, 0xffff0000, v65
	v_lshlrev_b32_e32 v4, 16, v52
	v_mul_f32_e32 v70, v25, v2
	v_and_b32_e32 v9, 0xffff0000, v52
	v_mul_f32_e32 v2, 0xbfb8aa3b, v4
	v_exp_f32_e32 v2, v2
	v_mul_f32_e32 v7, 0xbfb8aa3b, v9
	v_exp_f32_e32 v7, v7
	v_lshlrev_b32_e32 v11, 16, v53
	v_add_f32_e32 v2, 1.0, v2
	v_and_b32_e32 v43, 0xffff0000, v53
	v_rcp_f32_e32 v37, v2
	v_add_f32_e32 v2, 1.0, v7
	v_pk_add_f32 v[52:53], v[80:81], v[86:87]
	v_rcp_f32_e32 v88, v2
	v_mul_f32_e32 v2, 0xbfb8aa3b, v52
	v_exp_f32_e32 v2, v2
	v_mul_f32_e32 v7, 0xbfb8aa3b, v11
	v_exp_f32_e32 v7, v7
	v_mov_b32_e32 v63, v87
	v_pk_add_f32 v[64:65], v[80:81], v[86:87] neg_lo:[0,1] neg_hi:[0,1]
	v_pk_add_f32 v[66:67], v[70:71], v[62:63]
	v_pk_add_f32 v[62:63], v[70:71], v[62:63] neg_lo:[0,1] neg_hi:[0,1]
	v_mov_b32_e32 v69, v87
	v_add_f32_e32 v2, 1.0, v2
	v_mov_b32_e32 v67, v63
	v_mov_b32_e32 v64, v63
	v_pk_add_f32 v[62:63], v[74:75], v[68:69]
	v_pk_fma_f32 v[68:69], v[82:83], v[28:29], v[74:75] neg_lo:[1,0,0] neg_hi:[1,0,0]
	v_rcp_f32_e32 v34, v2
	v_add_f32_e32 v2, 1.0, v7
	v_pk_fma_f32 v[74:75], v[82:83], v[28:29], v[76:77] neg_lo:[1,0,0] neg_hi:[1,0,0]
	v_mul_f32_e32 v7, v69, v69
	v_mov_b32_e32 v53, v65
	v_pk_mul_f32 v[64:65], v[64:65], v[64:65]
	v_fmac_f32_e32 v7, v75, v75
	v_add_f32_e32 v7, v65, v7
	v_add_f32_e32 v7, v64, v7
	v_pk_add_f32 v[84:85], v[82:83], v[28:29]
	v_rcp_f32_e32 v80, v2
	v_add_f32_dpp v7, v7, v7 quad_perm:[1,0,3,2] row_mask:0xf bank_mask:0xf bound_ctrl:1
	v_mul_f32_e32 v2, 0xbfb8aa3b, v62
	v_exp_f32_e32 v2, v2
	v_add_f32_dpp v7, v7, v7 quad_perm:[2,3,0,1] row_mask:0xf bank_mask:0xf bound_ctrl:1
	v_mov_b32_e32 v85, v87
	v_pk_add_f32 v[70:71], v[76:77], v[84:85]
	v_add_f32_dpp v7, v7, v7 row_half_mirror row_mask:0xf bank_mask:0xf bound_ctrl:1
	v_add_f32_e32 v2, 1.0, v2
	v_rcp_f32_e32 v38, v2
	v_add_f32_dpp v7, v7, v7 row_mirror row_mask:0xf bank_mask:0xf bound_ctrl:1
	v_mul_f32_e32 v2, 0xbfb8aa3b, v70
	v_readlane_b32 s3, v7, 16
	v_readlane_b32 s2, v7, 0
	v_exp_f32_e32 v2, v2
	v_mov_b32_e32 v28, s3
	v_add_f32_e32 v28, s2, v28
	v_readlane_b32 s2, v7, 32
	v_add_f32_e32 v2, 1.0, v2
	v_mov_b32_e32 v63, v69
	v_add_f32_e32 v28, s2, v28
	v_readlane_b32 s2, v7, 48
	v_rcp_f32_e32 v2, v2
	v_mov_b32_e32 v71, v75
	v_add_f32_e32 v7, s2, v28
	v_fmamk_f32 v7, v7, 0x3b800000, v79
	v_mul_f32_e32 v28, 0x4b800000, v7
	v_cmp_gt_f32_e32 vcc, s11, v7
	s_add_i32 s8, s8, 2
	v_lshl_add_u64 v[72:73], v[72:73], 0, s[4:5]
	v_cndmask_b32_e32 v7, v7, v28, vcc
	v_rsq_f32_e32 v7, v7
	s_cmp_eq_u32 s8, 64
	v_mul_f32_e32 v28, 0x45800000, v7
	v_cndmask_b32_e32 v7, v7, v28, vcc
	v_pk_mul_f32 v[62:63], v[6:7], v[62:63]
	v_mov_b32_e32 v41, v7
	v_pk_mul_f32 v[62:63], v[62:63], v[38:39]
	s_nop 0
	v_add_f32_e32 v28, v62, v63
	v_pk_mul_f32 v[62:63], v[40:41], v[70:71]
	v_mul_f32_e32 v4, v28, v4
	v_pk_mul_f32 v[62:63], v[62:63], v[2:3]
	v_mul_f32_e32 v28, v37, v4
	v_add_f32_e32 v2, v62, v63
	v_mul_f32_e32 v2, v2, v9
	v_mov_b32_e32 v9, v7
	v_pk_mul_f32 v[52:53], v[8:9], v[52:53]
	v_mov_b32_e32 v37, v7
	v_pk_mul_f32 v[52:53], v[52:53], v[34:35]
	v_mul_f32_e32 v7, 0xbfb8aa3b, v43
	v_add_f32_e32 v4, v52, v53
	v_mul_f32_e32 v4, v4, v11
	v_mul_f32_e32 v9, v80, v4
	v_mul_f32_e32 v4, 0xbfb8aa3b, v66
	v_exp_f32_e32 v4, v4
	v_exp_f32_e32 v7, v7
	v_pk_mul_f32 v[52:53], v[36:37], v[66:67]
	v_mul_f32_e32 v2, v88, v2
	v_add_f32_e32 v4, 1.0, v4
	v_rcp_f32_e32 v4, v4
	v_add_f32_e32 v7, 1.0, v7
	v_rcp_f32_e32 v7, v7
	v_pk_mul_f32 v[52:53], v[52:53], v[4:5]
	s_nop 0
	v_add_f32_e32 v4, v52, v53
	v_mul_f32_e32 v4, v4, v43
	v_mul_f32_e32 v4, v7, v4
	v_cvt_pk_bf16_f32 v52, v28, v2
	v_cvt_pk_bf16_f32 v53, v9, v4
	global_store_dwordx2 v[72:73], v[52:53], off
	s_cbranch_scc1 .LBB0_593

; __device__ __forceinline__ unsigned pk2(float lo, float hi) { unsigned r; asm volatile("v_cvt_pk_bf16_f32 %0, %1, %2" : "=v"(r) : "v"(lo), "v"(hi)); return r; }
; __device__ __forceinline__ float bflo(unsigned w) { return __uint_as_float(w << 16); }
; __device__ __forceinline__ float bfhi(unsigned w) { return __uint_as_float(w & 0xffff0000u); }
; __device__ __forceinline__ float fsig0(float x) { return __builtin_amdgcn_rcpf(1.0f + __expf(-x)); }
; #define MN_LOAD(tk_) do { const int s_ = (tk_) & (SEQL - 1); hr = *(const u32x2*)(Hm + (size_t)(tk_) * 2048 + c); zr = *(const u32x2*)(Y0 + (size_t)(tk_) * 4096 + 2048 + c); \
;             _Pragma("unroll") for (int j = 0; j < 4; ++j) xr[j] = (s_ - 3 + j >= 0) ? *(const u32x2*)(XM + (size_t)((tk_) - 3 + j) * 2048 + c) : (u32x2){0u, 0u}; } while (0)
; __device__ void mnorm_phase(const Params& p) {
;     ...
;         for (int tt = 0; tt < 64; ++tt) {
;             const int tk = blk * 64 + tt;
;             const u32x2 hc_ = hr, zc_ = zr; const u32x2 xc0 = xr[0], xc1 = xr[1], xc2 = xr[2], xc3 = xr[3];
;             if (tt < 63) MN_LOAD(tk + 1);
;             float hv[4] = {bflo(hc_.x), bfhi(hc_.x), bflo(hc_.y), bfhi(hc_.y)};
;             const float mu = wave_sum_dpp(hv[0] + hv[1] + hv[2] + hv[3]) * (1.0f / 256.0f);
;             float d[4], sq = 0.f;
; #pragma unroll
;             for (int i = 0; i < 4; ++i) { d[i] = hv[i] - mu; sq += d[i] * d[i]; }
;             const float rs = rsqrtf(wave_sum_dpp(sq) * (1.0f / 256.0f) + 1e-6f);
;             float xmc[4] = {cbv[0], cbv[1], cbv[2], cbv[3]};
;             const u32x2 xs[4] = {xc0, xc1, xc2, xc3};
; #pragma unroll
;             for (int j = 0; j < 4; ++j) { xmc[0] += cw[j][0] * bflo(xs[j].x); xmc[1] += cw[j][1] * bfhi(xs[j].x); xmc[2] += cw[j][2] * bflo(xs[j].y); xmc[3] += cw[j][3] * bfhi(xs[j].y); }
;             const float z[4] = {bflo(zc_.x), bfhi(zc_.x), bflo(zc_.y), bfhi(zc_.y)};
;             float o[4];
; #pragma unroll
;             for (int i = 0; i < 4; ++i) o[i] = (d[i] * rs * gn[i] + skip[i] * xmc[i] * fsig0(xmc[i])) * z[i] * fsig0(z[i]);
;             u32x2 w; w.x = pk2(o[0], o[1]); w.y = pk2(o[2], o[3]); *(u32x2*)(Y0 + (size_t)tk * 4096 + 2048 + c) = w;
;         }
.LBB0_610:
	s_ashr_i32 s3, s2, 31
	s_lshl_b64 s[16:17], s[2:3], 12
	v_lshl_add_u64 v[76:77], v[32:33], 0, s[16:17]
	v_lshl_add_u64 v[74:75], v[32:33], 0, s[6:7]
	global_load_dwordx2 v[66:67], v[76:77], off
	global_load_dwordx2 v[64:65], v[74:75], off
	s_add_i32 s30, s13, s8
	s_add_i32 s30, s30, 4
	s_min_i32 s30, s30, 0x3fff
	s_ashr_i32 s31, s30, 31
	s_lshl_b64 s[32:33], s[30:31], 12
	s_lshl_b64 s[34:35], s[30:31], 13
	s_add_u32 s34, s10, s34
	s_addc_u32 s35, s12, s35
	s_add_u32 s34, s34, 0x1000
	s_addc_u32 s35, s35, 0
	v_lshl_add_u64 v[100:101], v[30:31], 0, s[32:33]
	v_lshl_add_u64 v[102:103], v[32:33], 0, s[32:33]
	v_lshl_add_u64 v[104:105], s[34:35], 0, v[26:27]
	global_load_dwordx2 v[106:107], v[100:101], off
	global_load_dwordx2 v[108:109], v[102:103], off
	global_load_dwordx2 v[110:111], v[104:105], off
	s_waitcnt vmcnt(12)
	v_lshlrev_b32_e32 v81, 16, v50
	v_and_b32_e32 v83, 0xffff0000, v50
	v_lshlrev_b32_e32 v85, 16, v51
	v_add_f32_e32 v2, v81, v83
	v_and_b32_e32 v51, 0xffff0000, v51
	v_add_f32_e32 v2, v2, v85
	v_add_f32_e32 v2, v2, v51
	s_waitcnt vmcnt(11)
	v_and_b32_e32 v89, 0xffff0000, v58
	v_and_b32_e32 v88, 0xffff0000, v54
	v_add_f32_dpp v2, v2, v2 quad_perm:[1,0,3,2] row_mask:0xf bank_mask:0xf bound_ctrl:1
	v_and_b32_e32 v7, 0xffff0000, v57
	v_pk_mul_f32 v[88:89], v[14:15], v[88:89]
	v_add_f32_dpp v2, v2, v2 quad_perm:[2,3,0,1] row_mask:0xf bank_mask:0xf bound_ctrl:1
	v_mov_b32_e32 v90, v88
	v_lshlrev_b32_e32 v93, 16, v59
	v_add_f32_dpp v2, v2, v2 row_half_mirror row_mask:0xf bank_mask:0xf bound_ctrl:1
	v_lshlrev_b32_e32 v92, 16, v55
	v_mov_b32_e32 v28, v89
	v_add_f32_dpp v2, v2, v2 row_mirror row_mask:0xf bank_mask:0xf bound_ctrl:1
	v_pk_mul_f32 v[92:93], v[44:45], v[92:93]
	v_readlane_b32 s7, v2, 16
	v_readlane_b32 s6, v2, 0
	v_and_b32_e32 v59, 0xffff0000, v59
	v_mov_b32_e32 v4, s7
	v_add_f32_e32 v87, s6, v4
	v_readlane_b32 s6, v2, 32
	v_and_b32_e32 v4, 0xffff0000, v56
	v_readlane_b32 s7, v2, 48
	v_lshlrev_b32_e32 v2, 16, v56
	v_mul_f32_e32 v86, v19, v4
	v_lshlrev_b32_e32 v4, 16, v57
	v_lshlrev_b32_e32 v57, 16, v58
	v_lshlrev_b32_e32 v56, 16, v54
	v_mov_b32_e32 v43, s6
	v_fma_f32 v2, v18, v2, v10
	v_pk_mul_f32 v[56:57], v[46:47], v[56:57]
	v_pk_add_f32 v[86:87], v[42:43], v[86:87]
	v_mov_b32_e32 v91, s7
	v_fma_f32 v4, v20, v4, v12
	v_add_f32_e32 v2, v2, v56
	v_pk_add_f32 v[86:87], v[86:87], v[90:91]
	v_and_b32_e32 v58, 0xffff0000, v55
	v_fma_f32 v7, v21, v7, v13
	v_add_f32_e32 v56, v2, v57
	v_pk_mul_f32 v[90:91], v[86:87], v[28:29]
	v_add_f32_e32 v2, v4, v92
	v_pk_mul_f32 v[54:55], v[16:17], v[58:59]
	v_add_f32_e32 v90, v2, v93
	v_add_f32_e32 v2, v7, v54
	v_add_f32_e32 v54, v2, v55
	s_waitcnt vmcnt(10)
	v_lshlrev_b32_e32 v2, 16, v60
	v_mul_f32_e32 v80, v22, v2
	v_and_b32_e32 v2, 0xffff0000, v60
	v_mul_f32_e32 v82, v23, v2
	v_lshlrev_b32_e32 v2, 16, v61
	v_mul_f32_e32 v84, v24, v2
	v_and_b32_e32 v2, 0xffff0000, v61
	v_lshlrev_b32_e32 v4, 16, v48
	v_mul_f32_e32 v50, v25, v2
	v_and_b32_e32 v9, 0xffff0000, v48
	v_mul_f32_e32 v2, 0xbfb8aa3b, v4
	v_exp_f32_e32 v2, v2
	v_mul_f32_e32 v7, 0xbfb8aa3b, v9
	v_exp_f32_e32 v7, v7
	v_lshlrev_b32_e32 v11, 16, v49
	v_add_f32_e32 v2, 1.0, v2
	v_and_b32_e32 v43, 0xffff0000, v49
	v_rcp_f32_e32 v37, v2
	v_add_f32_e32 v2, 1.0, v7
	v_pk_add_f32 v[48:49], v[84:85], v[90:91]
	v_rcp_f32_e32 v92, v2
	v_mul_f32_e32 v2, 0xbfb8aa3b, v48
	v_exp_f32_e32 v2, v2
	v_mul_f32_e32 v7, 0xbfb8aa3b, v11
	v_exp_f32_e32 v7, v7
	v_mov_b32_e32 v55, v91
	v_pk_add_f32 v[58:59], v[84:85], v[90:91] neg_lo:[0,1] neg_hi:[0,1]
	v_pk_add_f32 v[60:61], v[50:51], v[54:55]
	v_pk_add_f32 v[50:51], v[50:51], v[54:55] neg_lo:[0,1] neg_hi:[0,1]
	v_mov_b32_e32 v57, v91
	v_add_f32_e32 v2, 1.0, v2
	v_mov_b32_e32 v61, v51
	v_mov_b32_e32 v58, v51
	v_pk_add_f32 v[50:51], v[80:81], v[56:57]
	v_pk_fma_f32 v[56:57], v[86:87], v[28:29], v[80:81] neg_lo:[1,0,0] neg_hi:[1,0,0]
	v_rcp_f32_e32 v34, v2
	v_add_f32_e32 v2, 1.0, v7
	v_pk_fma_f32 v[80:81], v[86:87], v[28:29], v[82:83] neg_lo:[1,0,0] neg_hi:[1,0,0]
	v_mul_f32_e32 v7, v57, v57
	v_pk_mul_f32 v[54:55], v[58:59], v[58:59]
	v_fmac_f32_e32 v7, v81, v81
	v_add_f32_e32 v7, v55, v7
	v_add_f32_e32 v7, v54, v7
	v_pk_add_f32 v[88:89], v[86:87], v[28:29]
	v_rcp_f32_e32 v84, v2
	v_add_f32_dpp v7, v7, v7 quad_perm:[1,0,3,2] row_mask:0xf bank_mask:0xf bound_ctrl:1
	v_mul_f32_e32 v2, 0xbfb8aa3b, v50
	v_exp_f32_e32 v2, v2
	v_add_f32_dpp v7, v7, v7 quad_perm:[2,3,0,1] row_mask:0xf bank_mask:0xf bound_ctrl:1
	v_mov_b32_e32 v89, v91
	v_mov_b32_e32 v49, v59
	v_add_f32_dpp v7, v7, v7 row_half_mirror row_mask:0xf bank_mask:0xf bound_ctrl:1
	v_add_f32_e32 v2, 1.0, v2
	v_pk_add_f32 v[58:59], v[82:83], v[88:89]
	v_add_f32_dpp v7, v7, v7 row_mirror row_mask:0xf bank_mask:0xf bound_ctrl:1
	v_rcp_f32_e32 v38, v2
	v_readlane_b32 s7, v7, 16
	v_readlane_b32 s6, v7, 0
	v_mul_f32_e32 v2, 0xbfb8aa3b, v58
	v_mov_b32_e32 v28, s7
	v_add_f32_e32 v28, s6, v28
	v_readlane_b32 s6, v7, 32
	v_exp_f32_e32 v2, v2
	v_mov_b32_e32 v51, v57
	v_add_f32_e32 v28, s6, v28
	v_readlane_b32 s6, v7, 48
	v_add_f32_e32 v2, 1.0, v2
	v_rcp_f32_e32 v2, v2
	v_add_f32_e32 v7, s6, v28
	v_fmamk_f32 v7, v7, 0x3b800000, v79
	v_mul_f32_e32 v28, 0x4b800000, v7
	v_cmp_gt_f32_e32 vcc, s11, v7
	v_mov_b32_e32 v59, v81
	s_lshl_b64 s[6:7], s[2:3], 13
	v_cndmask_b32_e32 v7, v7, v28, vcc
	v_rsq_f32_e32 v7, v7
	s_add_u32 s6, s10, s6
	s_addc_u32 s7, s12, s7
	s_cmp_eq_u32 s8, 62
	v_mul_f32_e32 v28, 0x45800000, v7
	v_cndmask_b32_e32 v7, v7, v28, vcc
	v_pk_mul_f32 v[50:51], v[6:7], v[50:51]
	v_mov_b32_e32 v41, v7
	v_pk_mul_f32 v[50:51], v[50:51], v[38:39]
	s_waitcnt vmcnt(5)
	v_mov_b64_e32 v[54:55], v[62:63]
	v_add_f32_e32 v28, v50, v51
	v_pk_mul_f32 v[50:51], v[40:41], v[58:59]
	v_mul_f32_e32 v4, v28, v4
	v_pk_mul_f32 v[50:51], v[50:51], v[2:3]
	v_mul_f32_e32 v28, v37, v4
	v_add_f32_e32 v2, v50, v51
	v_mul_f32_e32 v2, v2, v9
	v_mov_b32_e32 v9, v7
	v_pk_mul_f32 v[48:49], v[8:9], v[48:49]
	v_mov_b32_e32 v37, v7
	v_pk_mul_f32 v[48:49], v[48:49], v[34:35]
	v_mul_f32_e32 v7, 0xbfb8aa3b, v43
	v_add_f32_e32 v4, v48, v49
	v_mul_f32_e32 v4, v4, v11
	v_mul_f32_e32 v9, v84, v4
	v_mul_f32_e32 v4, 0xbfb8aa3b, v60
	v_exp_f32_e32 v4, v4
	v_exp_f32_e32 v7, v7
	v_pk_mul_f32 v[48:49], v[36:37], v[60:61]
	v_lshl_add_u64 v[50:51], s[6:7], 0, v[26:27]
	v_add_f32_e32 v4, 1.0, v4
	v_rcp_f32_e32 v4, v4
	v_add_f32_e32 v7, 1.0, v7
	v_rcp_f32_e32 v7, v7
	v_add_co_u32_e32 v50, vcc, 0x1000, v50
	v_pk_mul_f32 v[48:49], v[48:49], v[4:5]
	v_mul_f32_e32 v2, v92, v2
	v_add_f32_e32 v4, v48, v49
	v_mul_f32_e32 v4, v4, v43
	v_mul_f32_e32 v4, v7, v4
	v_cvt_pk_bf16_f32 v48, v28, v2
	v_cvt_pk_bf16_f32 v49, v9, v4
	v_addc_co_u32_e32 v51, vcc, 0, v51, vcc
	global_store_dwordx2 v[50:51], v[48:49], off
	v_mov_b64_e32 v[50:51], v[70:71]
	v_mov_b64_e32 v[48:49], v[52:53]
	s_waitcnt vmcnt(4)
	v_mov_b64_e32 v[60:61], v[64:65]
	v_mov_b64_e32 v[58:59], v[66:67]
	v_mov_b64_e32 v[56:57], v[68:69]
	s_cbranch_scc1 .LBB0_604
; #define MN_LOAD(tk_) do { const int s_ = (tk_) & (SEQL - 1); hr = *(const u32x2*)(Hm + (size_t)(tk_) * 2048 + c); zr = *(const u32x2*)(Y0 + (size_t)(tk_) * 4096 + 2048 + c); \
;             _Pragma("unroll") for (int j = 0; j < 4; ++j) xr[j] = (s_ - 3 + j >= 0) ? *(const u32x2*)(XM + (size_t)((tk_) - 3 + j) * 2048 + c) : (u32x2){0u, 0u}; } while (0)
; __device__ void mnorm_phase(const Params& p) {
;     ...
;         MN_LOAD(blk * 64);
; #pragma unroll 2
;         for (int tt = 0; tt < 64; ++tt) {
;             const int tk = blk * 64 + tt;
;             const u32x2 hc_ = hr, zc_ = zr; const u32x2 xc0 = xr[0], xc1 = xr[1], xc2 = xr[2], xc3 = xr[3];
;             if (tt < 63) MN_LOAD(tk + 1);
	s_add_i32 s16, s2, 2
	s_ashr_i32 s17, s16, 31
	s_and_b32 s9, s16, 0xffe
	s_lshl_b64 s[6:7], s[16:17], 12
	s_lshl_b64 s[16:17], s[16:17], 13
	s_add_u32 s16, s10, s16
	s_addc_u32 s17, s12, s17
	v_lshl_add_u64 v[48:49], s[16:17], 0, v[26:27]
	v_lshl_add_u64 v[54:55], v[30:31], 0, s[6:7]
	v_add_co_u32_e32 v56, vcc, 0x1000, v48
	s_cmp_lt_u32 s9, 3
	s_nop 0
	v_addc_co_u32_e32 v57, vcc, 0, v49, vcc
	global_load_dwordx2 v[50:51], v[54:55], off
	global_load_dwordx2 v[48:49], v[56:57], off
	s_cbranch_scc1 .LBB0_614
	s_add_i32 s2, s2, -1
	s_ashr_i32 s3, s2, 31
	s_lshl_b64 s[2:3], s[2:3], 12
	v_lshl_add_u64 v[54:55], v[32:33], 0, s[2:3]
	global_load_dwordx2 v[56:57], v[54:55], off
	s_cmp_lg_u32 s9, 0
	s_cselect_b64 s[2:3], -1, 0
	s_cmp_eq_u32 s9, 0
	s_cbranch_scc0 .LBB0_615
